# up-proj K-loop LDS-DMA pieces rebalanced to four per phase (waits 8/6/8/6), on top of v82
# speedup vs baseline: 1.0034x; 1.0034x over previous
.LBB0_1303:
	s_add_i32 s48, s38, 2
	s_add_u32 s39, s36, 0xfffc0080
	s_addc_u32 s40, s37, -1
	s_add_i32 s49, 0, 0x10000
	s_cmp_eq_u32 s42, s38
	s_cselect_b32 s41, s9, s40
	s_cselect_b32 s40, s11, s39
	s_cselect_b32 s39, s44, s47
	s_cselect_b32 s38, s45, s46
	s_add_i32 s52, 0, 0x14000
	v_add_u32_e32 v152, s49, v138
	v_add_u32_e32 v168, s52, v138
	ds_read_b128 v[140:143], v152
	ds_read_b128 v[144:147], v152 offset:1024
	ds_read_b128 v[148:151], v152 offset:2048
	ds_read_b128 v[152:155], v152 offset:3072
	ds_read_b128 v[156:159], v168
	ds_read_b128 v[160:163], v168 offset:1024
	ds_read_b128 v[164:167], v168 offset:2048
	ds_read_b128 v[168:171], v168 offset:3072
	s_add_u32 s50, s46, 0x3ff80
	s_addc_u32 s51, s47, 0
	v_lshl_add_u64 v[208:209], s[50:51], 0, v[184:185]
	s_add_i32 m0, s23, 0x1c000
	v_lshl_add_u64 v[206:207], s[50:51], 0, v[128:129]
	ds_read_b128 v[172:175], v139
	ds_read_b128 v[176:179], v139 offset:1024
	ds_read_b128 v[180:183], v139 offset:2048
	ds_read_b128 v[186:189], v139 offset:3072
	ds_read_b128 v[190:193], v139 offset:4096
	ds_read_b128 v[194:197], v139 offset:5120
	ds_read_b128 v[198:201], v139 offset:6144
	ds_read_b128 v[202:205], v139 offset:7168
	global_load_lds_dwordx4 v[208:209], off
	s_add_i32 m0, s23, 0x1e000
	v_lshl_add_u64 v[208:209], s[36:37], 0, v[136:137]
	global_load_lds_dwordx4 v[206:207], off
	s_add_i32 m0, s17, 0xc000
	v_lshl_add_u64 v[206:207], s[36:37], 0, v[134:135]
	global_load_lds_dwordx4 v[208:209], off
	s_add_i32 m0, s17, 0xe000
	s_nop 0
	global_load_lds_dwordx4 v[206:207], off
	s_waitcnt vmcnt(8)
	s_waitcnt lgkmcnt(0)
	s_barrier
	s_setprio 1
	s_waitcnt lgkmcnt(0)
	v_mfma_f32_16x16x32_bf16 v[120:123], v[140:143], v[172:175], v[120:123]
	v_mfma_f32_16x16x32_bf16 v[124:127], v[148:151], v[172:175], v[124:127]
	v_mfma_f32_16x16x32_bf16 v[116:119], v[140:143], v[180:183], v[116:119]
	v_mfma_f32_16x16x32_bf16 v[112:115], v[148:151], v[180:183], v[112:115]
	v_mfma_f32_16x16x32_bf16 v[108:111], v[140:143], v[190:193], v[108:111]
	v_mfma_f32_16x16x32_bf16 v[104:107], v[148:151], v[190:193], v[104:107]
	v_mfma_f32_16x16x32_bf16 v[100:103], v[140:143], v[198:201], v[100:103]
	v_mfma_f32_16x16x32_bf16 v[96:99], v[148:151], v[198:201], v[96:99]
	v_mfma_f32_16x16x32_bf16 v[120:123], v[144:147], v[176:179], v[120:123]
	v_mfma_f32_16x16x32_bf16 v[124:127], v[152:155], v[176:179], v[124:127]
	v_mfma_f32_16x16x32_bf16 v[116:119], v[144:147], v[186:189], v[116:119]
	v_mfma_f32_16x16x32_bf16 v[112:115], v[152:155], v[186:189], v[112:115]
	v_mfma_f32_16x16x32_bf16 v[108:111], v[144:147], v[194:197], v[108:111]
	v_mfma_f32_16x16x32_bf16 v[104:107], v[152:155], v[194:197], v[104:107]
	v_mfma_f32_16x16x32_bf16 v[100:103], v[144:147], v[202:205], v[100:103]
	v_mfma_f32_16x16x32_bf16 v[96:99], v[152:155], v[202:205], v[96:99]
	s_setprio 0
	s_setprio 1
	v_mfma_f32_16x16x32_bf16 v[60:63], v[156:159], v[172:175], v[60:63]
	v_mfma_f32_16x16x32_bf16 v[56:59], v[164:167], v[172:175], v[56:59]
	v_mfma_f32_16x16x32_bf16 v[52:55], v[156:159], v[180:183], v[52:55]
	v_mfma_f32_16x16x32_bf16 v[48:51], v[164:167], v[180:183], v[48:51]
	v_mfma_f32_16x16x32_bf16 v[44:47], v[156:159], v[190:193], v[44:47]
	v_mfma_f32_16x16x32_bf16 v[40:43], v[164:167], v[190:193], v[40:43]
	v_mfma_f32_16x16x32_bf16 v[36:39], v[156:159], v[198:201], v[36:39]
	v_mfma_f32_16x16x32_bf16 v[32:35], v[164:167], v[198:201], v[32:35]
	v_mfma_f32_16x16x32_bf16 v[60:63], v[160:163], v[176:179], v[60:63]
	v_mfma_f32_16x16x32_bf16 v[56:59], v[168:171], v[176:179], v[56:59]
	v_mfma_f32_16x16x32_bf16 v[52:55], v[160:163], v[186:189], v[52:55]
	v_mfma_f32_16x16x32_bf16 v[48:51], v[168:171], v[186:189], v[48:51]
	v_mfma_f32_16x16x32_bf16 v[44:47], v[160:163], v[194:197], v[44:47]
	v_mfma_f32_16x16x32_bf16 v[40:43], v[168:171], v[194:197], v[40:43]
	v_mfma_f32_16x16x32_bf16 v[36:39], v[160:163], v[202:205], v[36:39]
	v_mfma_f32_16x16x32_bf16 v[32:35], v[168:171], v[202:205], v[32:35]
	s_setprio 0
	s_barrier
	s_add_i32 s49, s49, s23
	v_lshl_add_u64 v[206:207], s[38:39], 0, v[184:185]
	s_mov_b32 m0, s49
	ds_read_b128 v[172:175], v139 offset:16384
	ds_read_b128 v[176:179], v139 offset:17408
	ds_read_b128 v[180:183], v139 offset:18432
	ds_read_b128 v[186:189], v139 offset:19456
	ds_read_b128 v[190:193], v139 offset:20480
	ds_read_b128 v[194:197], v139 offset:21504
	ds_read_b128 v[198:201], v139 offset:22528
	ds_read_b128 v[202:205], v139 offset:23552
	global_load_lds_dwordx4 v[206:207], off
	s_add_i32 m0, s49, 0x2000
	v_lshl_add_u64 v[208:209], s[38:39], 0, v[128:129]
	v_lshl_add_u64 v[212:213], s[40:41], 0, v[130:131]
	global_load_lds_dwordx4 v[208:209], off
	v_lshl_add_u64 v[210:211], s[40:41], 0, v[132:133]
	s_mov_b32 m0, s17
	s_nop 0
	global_load_lds_dwordx4 v[210:211], off
	s_mov_b32 m0, s19
	s_nop 0
	global_load_lds_dwordx4 v[212:213], off
	s_waitcnt vmcnt(6)
	s_waitcnt lgkmcnt(0)
	s_barrier
	s_setprio 1
	s_waitcnt lgkmcnt(0)
	v_mfma_f32_16x16x32_bf16 v[92:95], v[140:143], v[172:175], v[92:95]
	v_mfma_f32_16x16x32_bf16 v[88:91], v[148:151], v[172:175], v[88:91]
	v_mfma_f32_16x16x32_bf16 v[84:87], v[140:143], v[180:183], v[84:87]
	v_mfma_f32_16x16x32_bf16 v[80:83], v[148:151], v[180:183], v[80:83]
	v_mfma_f32_16x16x32_bf16 v[76:79], v[140:143], v[190:193], v[76:79]
	v_mfma_f32_16x16x32_bf16 v[72:75], v[148:151], v[190:193], v[72:75]
	v_mfma_f32_16x16x32_bf16 v[68:71], v[140:143], v[198:201], v[68:71]
	v_mfma_f32_16x16x32_bf16 v[64:67], v[148:151], v[198:201], v[64:67]
	v_mfma_f32_16x16x32_bf16 v[92:95], v[144:147], v[176:179], v[92:95]
	v_mfma_f32_16x16x32_bf16 v[88:91], v[152:155], v[176:179], v[88:91]
	v_mfma_f32_16x16x32_bf16 v[84:87], v[144:147], v[186:189], v[84:87]
	v_mfma_f32_16x16x32_bf16 v[80:83], v[152:155], v[186:189], v[80:83]
	v_mfma_f32_16x16x32_bf16 v[76:79], v[144:147], v[194:197], v[76:79]
	v_mfma_f32_16x16x32_bf16 v[72:75], v[152:155], v[194:197], v[72:75]
	v_mfma_f32_16x16x32_bf16 v[68:71], v[144:147], v[202:205], v[68:71]
	v_mfma_f32_16x16x32_bf16 v[64:67], v[152:155], v[202:205], v[64:67]
	s_setprio 0
	s_setprio 1
	v_mfma_f32_16x16x32_bf16 v[28:31], v[156:159], v[172:175], v[28:31]
	v_mfma_f32_16x16x32_bf16 v[24:27], v[164:167], v[172:175], v[24:27]
	v_mfma_f32_16x16x32_bf16 v[20:23], v[156:159], v[180:183], v[20:23]
	v_mfma_f32_16x16x32_bf16 v[16:19], v[164:167], v[180:183], v[16:19]
	v_mfma_f32_16x16x32_bf16 v[12:15], v[156:159], v[190:193], v[12:15]
	v_mfma_f32_16x16x32_bf16 v[8:11], v[164:167], v[190:193], v[8:11]
	v_mfma_f32_16x16x32_bf16 v[4:7], v[156:159], v[198:201], v[4:7]
	v_mfma_f32_16x16x32_bf16 v[0:3], v[164:167], v[198:201], v[0:3]
	v_mfma_f32_16x16x32_bf16 v[28:31], v[160:163], v[176:179], v[28:31]
	v_mfma_f32_16x16x32_bf16 v[24:27], v[168:171], v[176:179], v[24:27]
	v_mfma_f32_16x16x32_bf16 v[20:23], v[160:163], v[186:189], v[20:23]
	v_mfma_f32_16x16x32_bf16 v[16:19], v[168:171], v[186:189], v[16:19]
	v_mfma_f32_16x16x32_bf16 v[12:15], v[160:163], v[194:197], v[12:15]
	v_mfma_f32_16x16x32_bf16 v[8:11], v[168:171], v[194:197], v[8:11]
	v_mfma_f32_16x16x32_bf16 v[4:7], v[160:163], v[202:205], v[4:7]
	v_mfma_f32_16x16x32_bf16 v[0:3], v[168:171], v[202:205], v[0:3]
	s_setprio 0
	s_barrier
	s_add_i32 s49, 0, 0x18000
	s_add_i32 s50, 0, 0x1c000
	v_add_u32_e32 v152, s49, v138
	v_add_u32_e32 v168, s50, v138
	ds_read_b128 v[140:143], v152
	ds_read_b128 v[144:147], v152 offset:1024
	ds_read_b128 v[148:151], v152 offset:2048
	ds_read_b128 v[152:155], v152 offset:3072
	ds_read_b128 v[156:159], v168
	ds_read_b128 v[160:163], v168 offset:1024
	ds_read_b128 v[164:167], v168 offset:2048
	ds_read_b128 v[168:171], v168 offset:3072
	s_add_u32 s50, s38, 0x40000
	s_addc_u32 s51, s39, 0
	s_add_u32 s40, s40, 0x40000
	s_addc_u32 s41, s41, 0
	v_lshl_add_u64 v[214:215], s[50:51], 0, v[184:185]
	s_add_i32 m0, s23, 0x14000
	v_lshl_add_u64 v[216:217], s[50:51], 0, v[128:129]
	ds_read_b128 v[172:175], v139 offset:32768
	ds_read_b128 v[176:179], v139 offset:33792
	ds_read_b128 v[180:183], v139 offset:34816
	ds_read_b128 v[186:189], v139 offset:35840
	ds_read_b128 v[190:193], v139 offset:36864
	ds_read_b128 v[194:197], v139 offset:37888
	ds_read_b128 v[198:201], v139 offset:38912
	ds_read_b128 v[202:205], v139 offset:39936
	global_load_lds_dwordx4 v[214:215], off
	s_add_i32 m0, s23, 0x16000
	v_lshl_add_u64 v[214:215], s[40:41], 0, v[132:133]
	global_load_lds_dwordx4 v[216:217], off
	s_mov_b32 m0, s27
	v_lshl_add_u64 v[216:217], s[40:41], 0, v[130:131]
	global_load_lds_dwordx4 v[214:215], off
	s_mov_b32 m0, s28
	s_nop 0
	global_load_lds_dwordx4 v[216:217], off
	s_waitcnt vmcnt(8)
	s_waitcnt lgkmcnt(0)
	s_barrier
	s_setprio 1
	s_waitcnt lgkmcnt(0)
	v_mfma_f32_16x16x32_bf16 v[120:123], v[140:143], v[172:175], v[120:123]
	v_mfma_f32_16x16x32_bf16 v[124:127], v[148:151], v[172:175], v[124:127]
	v_mfma_f32_16x16x32_bf16 v[116:119], v[140:143], v[180:183], v[116:119]
	v_mfma_f32_16x16x32_bf16 v[112:115], v[148:151], v[180:183], v[112:115]
	v_mfma_f32_16x16x32_bf16 v[108:111], v[140:143], v[190:193], v[108:111]
	v_mfma_f32_16x16x32_bf16 v[104:107], v[148:151], v[190:193], v[104:107]
	v_mfma_f32_16x16x32_bf16 v[100:103], v[140:143], v[198:201], v[100:103]
	v_mfma_f32_16x16x32_bf16 v[96:99], v[148:151], v[198:201], v[96:99]
	v_mfma_f32_16x16x32_bf16 v[120:123], v[144:147], v[176:179], v[120:123]
	v_mfma_f32_16x16x32_bf16 v[124:127], v[152:155], v[176:179], v[124:127]
	v_mfma_f32_16x16x32_bf16 v[116:119], v[144:147], v[186:189], v[116:119]
	v_mfma_f32_16x16x32_bf16 v[112:115], v[152:155], v[186:189], v[112:115]
	v_mfma_f32_16x16x32_bf16 v[108:111], v[144:147], v[194:197], v[108:111]
	v_mfma_f32_16x16x32_bf16 v[104:107], v[152:155], v[194:197], v[104:107]
	v_mfma_f32_16x16x32_bf16 v[100:103], v[144:147], v[202:205], v[100:103]
	v_mfma_f32_16x16x32_bf16 v[96:99], v[152:155], v[202:205], v[96:99]
	s_setprio 0
	s_setprio 1
	v_mfma_f32_16x16x32_bf16 v[60:63], v[156:159], v[172:175], v[60:63]
	v_mfma_f32_16x16x32_bf16 v[56:59], v[164:167], v[172:175], v[56:59]
	v_mfma_f32_16x16x32_bf16 v[52:55], v[156:159], v[180:183], v[52:55]
	v_mfma_f32_16x16x32_bf16 v[48:51], v[164:167], v[180:183], v[48:51]
	v_mfma_f32_16x16x32_bf16 v[44:47], v[156:159], v[190:193], v[44:47]
	v_mfma_f32_16x16x32_bf16 v[40:43], v[164:167], v[190:193], v[40:43]
	v_mfma_f32_16x16x32_bf16 v[36:39], v[156:159], v[198:201], v[36:39]
	v_mfma_f32_16x16x32_bf16 v[32:35], v[164:167], v[198:201], v[32:35]
	v_mfma_f32_16x16x32_bf16 v[60:63], v[160:163], v[176:179], v[60:63]
	v_mfma_f32_16x16x32_bf16 v[56:59], v[168:171], v[176:179], v[56:59]
	v_mfma_f32_16x16x32_bf16 v[52:55], v[160:163], v[186:189], v[52:55]
	v_mfma_f32_16x16x32_bf16 v[48:51], v[168:171], v[186:189], v[48:51]
	v_mfma_f32_16x16x32_bf16 v[44:47], v[160:163], v[194:197], v[44:47]
	v_mfma_f32_16x16x32_bf16 v[40:43], v[168:171], v[194:197], v[40:43]
	v_mfma_f32_16x16x32_bf16 v[36:39], v[160:163], v[202:205], v[36:39]
	v_mfma_f32_16x16x32_bf16 v[32:35], v[168:171], v[202:205], v[32:35]
	s_setprio 0
	s_barrier
	s_add_i32 s40, s49, s23
	v_lshl_add_u64 v[206:207], v[206:207], 0, s[30:31]
	s_mov_b32 m0, s40
	ds_read_b128 v[172:175], v139 offset:49152
	ds_read_b128 v[176:179], v139 offset:50176
	ds_read_b128 v[180:183], v139 offset:51200
	ds_read_b128 v[186:189], v139 offset:52224
	ds_read_b128 v[190:193], v139 offset:53248
	ds_read_b128 v[194:197], v139 offset:54272
	ds_read_b128 v[198:201], v139 offset:55296
	ds_read_b128 v[202:205], v139 offset:56320
	global_load_lds_dwordx4 v[206:207], off
	s_add_i32 m0, s40, 0x2000
	v_lshl_add_u64 v[206:207], v[208:209], 0, s[30:31]
	s_nop 0
	global_load_lds_dwordx4 v[206:207], off
	v_lshl_add_u64 v[206:207], v[210:211], 0, s[30:31]
	s_mov_b32 m0, s34
	s_nop 0
	global_load_lds_dwordx4 v[206:207], off
	v_lshl_add_u64 v[206:207], v[212:213], 0, s[30:31]
	s_mov_b32 m0, s35
	s_nop 0
	global_load_lds_dwordx4 v[206:207], off
	s_waitcnt vmcnt(6)
	s_waitcnt lgkmcnt(0)
	s_barrier
	s_setprio 1
	s_waitcnt lgkmcnt(0)
	v_mfma_f32_16x16x32_bf16 v[92:95], v[140:143], v[172:175], v[92:95]
	v_mfma_f32_16x16x32_bf16 v[88:91], v[148:151], v[172:175], v[88:91]
	v_mfma_f32_16x16x32_bf16 v[84:87], v[140:143], v[180:183], v[84:87]
	v_mfma_f32_16x16x32_bf16 v[80:83], v[148:151], v[180:183], v[80:83]
	v_mfma_f32_16x16x32_bf16 v[76:79], v[140:143], v[190:193], v[76:79]
	v_mfma_f32_16x16x32_bf16 v[72:75], v[148:151], v[190:193], v[72:75]
	v_mfma_f32_16x16x32_bf16 v[68:71], v[140:143], v[198:201], v[68:71]
	v_mfma_f32_16x16x32_bf16 v[64:67], v[148:151], v[198:201], v[64:67]
	v_mfma_f32_16x16x32_bf16 v[92:95], v[144:147], v[176:179], v[92:95]
	v_mfma_f32_16x16x32_bf16 v[88:91], v[152:155], v[176:179], v[88:91]
	v_mfma_f32_16x16x32_bf16 v[84:87], v[144:147], v[186:189], v[84:87]
	v_mfma_f32_16x16x32_bf16 v[80:83], v[152:155], v[186:189], v[80:83]
	v_mfma_f32_16x16x32_bf16 v[76:79], v[144:147], v[194:197], v[76:79]
	v_mfma_f32_16x16x32_bf16 v[72:75], v[152:155], v[194:197], v[72:75]
	v_mfma_f32_16x16x32_bf16 v[68:71], v[144:147], v[202:205], v[68:71]
	v_mfma_f32_16x16x32_bf16 v[64:67], v[152:155], v[202:205], v[64:67]
	s_setprio 0
	s_setprio 1
	v_mfma_f32_16x16x32_bf16 v[28:31], v[156:159], v[172:175], v[28:31]
	v_mfma_f32_16x16x32_bf16 v[24:27], v[164:167], v[172:175], v[24:27]
	v_mfma_f32_16x16x32_bf16 v[20:23], v[156:159], v[180:183], v[20:23]
	v_mfma_f32_16x16x32_bf16 v[16:19], v[164:167], v[180:183], v[16:19]
	v_mfma_f32_16x16x32_bf16 v[12:15], v[156:159], v[190:193], v[12:15]
	v_mfma_f32_16x16x32_bf16 v[8:11], v[164:167], v[190:193], v[8:11]
	v_mfma_f32_16x16x32_bf16 v[4:7], v[156:159], v[198:201], v[4:7]
	v_mfma_f32_16x16x32_bf16 v[0:3], v[164:167], v[198:201], v[0:3]
	v_mfma_f32_16x16x32_bf16 v[28:31], v[160:163], v[176:179], v[28:31]
	v_mfma_f32_16x16x32_bf16 v[24:27], v[168:171], v[176:179], v[24:27]
	v_mfma_f32_16x16x32_bf16 v[20:23], v[160:163], v[186:189], v[20:23]
	v_mfma_f32_16x16x32_bf16 v[16:19], v[168:171], v[186:189], v[16:19]
	v_mfma_f32_16x16x32_bf16 v[12:15], v[160:163], v[194:197], v[12:15]
	v_mfma_f32_16x16x32_bf16 v[8:11], v[168:171], v[194:197], v[8:11]
	v_mfma_f32_16x16x32_bf16 v[4:7], v[160:163], v[202:205], v[4:7]
	v_mfma_f32_16x16x32_bf16 v[0:3], v[168:171], v[202:205], v[0:3]
	s_setprio 0
	s_barrier
	s_add_u32 s46, s46, 0x100
	s_addc_u32 s47, s47, 0
	s_add_u32 s36, s36, 0x100
	s_addc_u32 s37, s37, 0
	s_cmp_ge_i32 s48, s29
	s_mov_b32 s38, s48
	s_cbranch_scc0 .LBB0_1303
